# all four weight-transpose loops (P0, P1 tail, P8 front, P9 tail) rewritten by hand: 32 row loads in flight per item instead of serialized round trips
# speedup vs baseline: 1.0430x; 1.0430x over previous
; #define LAS __attribute__((address_space(3)))
; __device__ __forceinline__ void transpose_item(const float* W, int K, int N, const float* gain, bf16_t* WT, int mode, LAS float* scr, int item, int lane) {
;     const int nblk = N / 32, kb = item / nblk, nb = item % nblk, k0 = 64 * kb, n0 = 32 * nb;
; #pragma unroll
;     for (int i = 0; i < 32; ++i) { const int kk = 2 * i + (lane >> 5); float w = W[(size_t)(k0 + kk) * N + n0 + (lane & 31)]; if (gain) w *= gain[k0 + kk]; scr[kk * 33 + (lane & 31)] = w; }
; __device__ __forceinline__ void phase0(const Ctx& C) {
;     ...
;     for (int it = gw; it < NIT; it += NGW) {
;         int r = it;
;         if (r < 16) { transpose_item(C.in[10], 64, 512, nullptr, wdecT, 0, scr, r, lane); continue; } r -= 16;
;         if (r < 16) { transpose_item(C.in[12], 64, 512, nullptr, waaaT, 0, scr, r, lane); continue; } r -= 16;
;         if (r < 32) { transpose_item(C.in[13], 128, 512, nullptr, wgateT, 0, scr, r, lane); continue; } r -= 32;
;         if (r < I1) { transpose_item(C.in[3], D_, FF_, C.in[2], W13, 1, scr, r, lane); continue; } r -= I1;
;         transpose_item(C.in[4], D_, FF_, C.in[2], W13, 2, scr, r, lane);
.LBB0_5:
	s_or_b64 exec, exec, s[6:7]
	v_readlane_b32 s0, v254, 1
	v_readlane_b32 s1, v254, 2
	s_load_dwordx16 s[36:51], s[0:1], 0x0
	s_load_dwordx16 s[4:19], s[0:1], 0x40
	s_lshr_b32 s80, s55, 6
	s_add_u32 s0, s26, 0x5800000
	s_addc_u32 s1, s27, 0
	v_and_b32_e32 v193, 63, v0
	s_waitcnt lgkmcnt(0)
	v_writelane_b32 v254, s4, 6
	s_nop 1
	v_writelane_b32 v254, s5, 7
	v_writelane_b32 v254, s6, 8
	v_writelane_b32 v254, s7, 9
	v_writelane_b32 v254, s8, 10
	v_writelane_b32 v254, s9, 11
	v_writelane_b32 v254, s10, 12
	v_writelane_b32 v254, s11, 13
	v_writelane_b32 v254, s12, 14
	v_writelane_b32 v254, s13, 15
	v_writelane_b32 v254, s14, 16
	v_writelane_b32 v254, s15, 17
	v_writelane_b32 v254, s16, 18
	v_writelane_b32 v254, s17, 19
	v_writelane_b32 v254, s18, 20
	v_writelane_b32 v254, s19, 21
	v_writelane_b32 v254, s0, 22
	s_nop 1
	v_writelane_b32 v254, s1, 23
	s_add_u32 s0, s26, 0xf600000
	s_addc_u32 s1, s27, 0
	v_writelane_b32 v254, s0, 24
	s_cmp_lt_i32 s76, 1
	s_nop 0
	v_writelane_b32 v254, s1, 25
	v_writelane_b32 v254, s36, 26
	s_cselect_b64 s[0:1], -1, 0
	s_cmp_gt_i32 s77, 0
	v_writelane_b32 v254, s37, 27
	v_writelane_b32 v254, s38, 28
	v_writelane_b32 v254, s39, 29
	v_writelane_b32 v254, s40, 30
	v_writelane_b32 v254, s41, 31
	v_writelane_b32 v254, s42, 32
	v_writelane_b32 v254, s43, 33
	v_writelane_b32 v254, s44, 34
	v_writelane_b32 v254, s45, 35
	v_writelane_b32 v254, s46, 36
	v_writelane_b32 v254, s47, 37
	v_writelane_b32 v254, s48, 38
	s_cselect_b64 s[2:3], -1, 0
	v_writelane_b32 v254, s49, 39
	s_and_b64 s[12:13], s[0:1], s[2:3]
	v_writelane_b32 v254, s50, 40
	s_andn2_b64 vcc, exec, s[12:13]
	v_writelane_b32 v254, s51, 41
	s_cbranch_vccnz .LBB0_188
	s_lshl_b32 s0, s94, 3
	s_add_i32 s10, s80, s0
	s_lshl_b32 s0, s88, 3
	s_cmpk_gt_i32 s10, 0xb3f
	s_cbranch_scc1 .LBB0_153
	s_waitcnt lgkmcnt(0)
	s_mov_b32 s2, s10
	s_mov_b32 s3, s0
	v_readlane_b32 s100, v254, 1
	v_readlane_b32 s101, v254, 2
	v_and_b32_e32 v1, 31, v193
	v_lshrrev_b32_e32 v2, 5, v193
	v_and_b32_e32 v3, 7, v193
	v_lshrrev_b32_e32 v4, 3, v193
	s_mul_i32 s16, s80, 0x2100
	v_mad_u32_u24 v5, v2, 33, v1
	v_lshl_add_u32 v5, v5, 2, s16
	v_mul_u32_u24_e32 v6, 0x108, v3
	v_add_u32_e32 v6, v6, v4
	v_lshl_add_u32 v6, v6, 2, s16
.Lmy_c0_loop:
	s_cmp_ge_i32 s2, 0xb40
	s_cbranch_scc1 .Lmy_c0_exit
	s_cmp_ge_i32 s2, 0x10
	s_cbranch_scc1 .Lmy_c0_seg1
	s_mov_b32 s15, s2
	s_mov_b32 s16, 0x10000001
	s_mul_hi_u32 s14, s15, s16
	s_mul_i32 s16, s14, 16
	s_sub_i32 s15, s15, s16
	s_load_dwordx2 s[4:5], s[100:101], 0x50
	s_mov_b64 s[18:19], 0
	s_add_u32 s52, s26, 0xfe00000
	s_addc_u32 s53, s27, 0
	s_mov_b32 s6, 0x800
	s_mov_b32 s54, 0x80
	s_mov_b32 s56, 0
	s_waitcnt lgkmcnt(0)
	s_branch .Lmy_c0_item
.Lmy_c0_seg1:
	s_cmp_ge_i32 s2, 0x20
	s_cbranch_scc1 .Lmy_c0_seg2
	s_sub_i32 s15, s2, 0x10
	s_mov_b32 s16, 0x10000001
	s_mul_hi_u32 s14, s15, s16
	s_mul_i32 s16, s14, 16
	s_sub_i32 s15, s15, s16
	s_load_dwordx2 s[4:5], s[100:101], 0x60
	s_mov_b64 s[18:19], 0
	s_add_u32 s52, s26, 0xfe10000
	s_addc_u32 s53, s27, 0
	s_mov_b32 s6, 0x800
	s_mov_b32 s54, 0x80
	s_mov_b32 s56, 0
	s_waitcnt lgkmcnt(0)
	s_branch .Lmy_c0_item
.Lmy_c0_seg2:
	s_cmp_ge_i32 s2, 0x40
	s_cbranch_scc1 .Lmy_c0_seg3
	s_sub_i32 s15, s2, 0x20
	s_mov_b32 s16, 0x10000001
	s_mul_hi_u32 s14, s15, s16
	s_mul_i32 s16, s14, 16
	s_sub_i32 s15, s15, s16
	s_load_dwordx2 s[4:5], s[100:101], 0x68
	s_mov_b64 s[18:19], 0
	s_add_u32 s52, s26, 0xfe20000
	s_addc_u32 s53, s27, 0
	s_mov_b32 s6, 0x800
	s_mov_b32 s54, 0x100
	s_mov_b32 s56, 0
	s_waitcnt lgkmcnt(0)
	s_branch .Lmy_c0_item
.Lmy_c0_seg3:
	s_cmp_ge_i32 s2, 0x5c0
	s_cbranch_scc1 .Lmy_c0_seg4
	s_sub_i32 s15, s2, 0x40
	s_mov_b32 s16, 0x2e8ba2f
	s_mul_hi_u32 s14, s15, s16
	s_mul_i32 s16, s14, 88
	s_sub_i32 s15, s15, s16
	s_load_dwordx2 s[4:5], s[100:101], 0x18
	s_load_dwordx2 s[18:19], s[100:101], 0x10
	s_add_u32 s52, s26, 0x9800000
	s_addc_u32 s53, s27, 0
	s_mov_b32 s6, 0x2c00
	s_mov_b32 s54, 0x800
	s_mov_b32 s56, 1
	s_waitcnt lgkmcnt(0)
	s_branch .Lmy_c0_item
.Lmy_c0_seg4:
	s_sub_i32 s15, s2, 0x5c0
	s_mov_b32 s16, 0x2e8ba2f
	s_mul_hi_u32 s14, s15, s16
	s_mul_i32 s16, s14, 88
	s_sub_i32 s15, s15, s16
	s_load_dwordx2 s[4:5], s[100:101], 0x20
	s_load_dwordx2 s[18:19], s[100:101], 0x10
	s_add_u32 s52, s26, 0x9800000
	s_addc_u32 s53, s27, 0
	s_mov_b32 s6, 0x2c00
	s_mov_b32 s54, 0x800
	s_mov_b32 s56, 2
	s_waitcnt lgkmcnt(0)
.Lmy_c0_item:
	s_lshl_b32 s14, s14, 6
	s_lshl_b32 s15, s15, 5
	v_mul_lo_u32 v7, v2, s6
	v_lshl_add_u32 v7, v1, 2, v7
	s_cmp_eq_u64 s[18:19], 0
	s_cbranch_scc1 .Lmy_c0_nog
	v_lshlrev_b32_e32 v9, 3, v3
	v_add_lshl_u32 v9, v9, s14, 2
	global_load_dwordx4 v[52:55], v9, s[18:19]
	global_load_dwordx4 v[56:59], v9, s[18:19] offset:16
	s_branch .Lmy_c0_g

; #define LAS __attribute__((address_space(3)))
; __device__ __forceinline__ unsigned pk2(float lo, float hi) { const f32x2 v = {lo, hi}; const bf16x2_t b = __builtin_convertvector(v, bf16x2_t); return __builtin_bit_cast(unsigned, b); }
; __device__ __forceinline__ int map13(int hidden, int which) { return (hidden >> 7) * 256 + which * 128 + (hidden & 127); }
; __device__ __forceinline__ void transpose_item(const float* W, int K, int N, const float* gain, bf16_t* WT, int mode, LAS float* scr, int item, int lane) {
;     const int nblk = N / 32, kb = item / nblk, nb = item % nblk, k0 = 64 * kb, n0 = 32 * nb;
; #pragma unroll
;     for (int i = 0; i < 32; ++i) { const int kk = 2 * i + (lane >> 5); float w = W[(size_t)(k0 + kk) * N + n0 + (lane & 31)]; if (gain) w *= gain[k0 + kk]; scr[kk * 33 + (lane & 31)] = w; }
;     asm volatile("s_waitcnt lgkmcnt(0)" ::: "memory");
;     const int c = lane & 7;
; #pragma unroll
;     for (int j = 0; j < 4; ++j) { const int n = (lane >> 3) + 8 * j; const LAS float* s = scr + (8 * c) * 33 + n;
;         u32x4 o; o.x = pk2(s[0 * 33], s[1 * 33]); o.y = pk2(s[2 * 33], s[3 * 33]); o.z = pk2(s[4 * 33], s[5 * 33]); o.w = pk2(s[6 * 33], s[7 * 33]);
;         const int row = (mode == 0) ? (n0 + n) : map13(n0 + n, mode - 1);
;         *(u32x4*)(WT + (size_t)row * K + k0 + 8 * c) = o; }
.Lmy_c0_g:
	s_mul_i32 s18, s14, s6
	s_mul_hi_u32 s19, s14, s6
	s_lshl_b32 s16, s15, 2
	s_add_u32 s18, s18, s16
	s_addc_u32 s19, s19, 0
	s_add_u32 s18, s18, s4
	s_addc_u32 s19, s19, s5
	s_lshl_b32 s16, s6, 1
	global_load_dword v20, v7, s[18:19]
	s_add_u32 s18, s18, s16
	s_addc_u32 s19, s19, 0
	global_load_dword v21, v7, s[18:19]
	s_add_u32 s18, s18, s16
	s_addc_u32 s19, s19, 0
	global_load_dword v22, v7, s[18:19]
	s_add_u32 s18, s18, s16
	s_addc_u32 s19, s19, 0
	global_load_dword v23, v7, s[18:19]
	s_add_u32 s18, s18, s16
	s_addc_u32 s19, s19, 0
	global_load_dword v24, v7, s[18:19]
	s_add_u32 s18, s18, s16
	s_addc_u32 s19, s19, 0
	global_load_dword v25, v7, s[18:19]
	s_add_u32 s18, s18, s16
	s_addc_u32 s19, s19, 0
	global_load_dword v26, v7, s[18:19]
	s_add_u32 s18, s18, s16
	s_addc_u32 s19, s19, 0
	global_load_dword v27, v7, s[18:19]
	s_add_u32 s18, s18, s16
	s_addc_u32 s19, s19, 0
	global_load_dword v28, v7, s[18:19]
	s_add_u32 s18, s18, s16
	s_addc_u32 s19, s19, 0
	global_load_dword v29, v7, s[18:19]
	s_add_u32 s18, s18, s16
	s_addc_u32 s19, s19, 0
	global_load_dword v30, v7, s[18:19]
	s_add_u32 s18, s18, s16
	s_addc_u32 s19, s19, 0
	global_load_dword v31, v7, s[18:19]
	s_add_u32 s18, s18, s16
	s_addc_u32 s19, s19, 0
	global_load_dword v32, v7, s[18:19]
	s_add_u32 s18, s18, s16
	s_addc_u32 s19, s19, 0
	global_load_dword v33, v7, s[18:19]
	s_add_u32 s18, s18, s16
	s_addc_u32 s19, s19, 0
	global_load_dword v34, v7, s[18:19]
	s_add_u32 s18, s18, s16
	s_addc_u32 s19, s19, 0
	global_load_dword v35, v7, s[18:19]
	s_add_u32 s18, s18, s16
	s_addc_u32 s19, s19, 0
	global_load_dword v36, v7, s[18:19]
	s_add_u32 s18, s18, s16
	s_addc_u32 s19, s19, 0
	global_load_dword v37, v7, s[18:19]
	s_add_u32 s18, s18, s16
	s_addc_u32 s19, s19, 0
	global_load_dword v38, v7, s[18:19]
	s_add_u32 s18, s18, s16
	s_addc_u32 s19, s19, 0
	global_load_dword v39, v7, s[18:19]
	s_add_u32 s18, s18, s16
	s_addc_u32 s19, s19, 0
	global_load_dword v40, v7, s[18:19]
	s_add_u32 s18, s18, s16
	s_addc_u32 s19, s19, 0
	global_load_dword v41, v7, s[18:19]
	s_add_u32 s18, s18, s16
	s_addc_u32 s19, s19, 0
	global_load_dword v42, v7, s[18:19]
	s_add_u32 s18, s18, s16
	s_addc_u32 s19, s19, 0
	global_load_dword v43, v7, s[18:19]
	s_add_u32 s18, s18, s16
	s_addc_u32 s19, s19, 0
	global_load_dword v44, v7, s[18:19]
	s_add_u32 s18, s18, s16
	s_addc_u32 s19, s19, 0
	global_load_dword v45, v7, s[18:19]
	s_add_u32 s18, s18, s16
	s_addc_u32 s19, s19, 0
	global_load_dword v46, v7, s[18:19]
	s_add_u32 s18, s18, s16
	s_addc_u32 s19, s19, 0
	global_load_dword v47, v7, s[18:19]
	s_add_u32 s18, s18, s16
	s_addc_u32 s19, s19, 0
	global_load_dword v48, v7, s[18:19]
	s_add_u32 s18, s18, s16
	s_addc_u32 s19, s19, 0
	global_load_dword v49, v7, s[18:19]
	s_add_u32 s18, s18, s16
	s_addc_u32 s19, s19, 0
	global_load_dword v50, v7, s[18:19]
	s_add_u32 s18, s18, s16
	s_addc_u32 s19, s19, 0
	global_load_dword v51, v7, s[18:19]
	v_add_u32_e32 v10, s15, v4
	s_cmp_eq_u32 s56, 0
	s_cselect_b64 vcc, -1, 0
	s_add_i32 s16, s56, -1
	s_lshl_b32 s16, s16, 7
	v_lshlrev_b32_e32 v11, 3, v3
	v_add_lshl_u32 v11, v11, s14, 1
	v_add_u32_e32 v16, 0, v10
	v_lshrrev_b32_e32 v17, 7, v16
	v_and_b32_e32 v18, 0x7f, v16
	v_lshl_add_u32 v17, v17, 8, v18
	v_add_u32_e32 v17, s16, v17
	v_cndmask_b32_e32 v16, v17, v16, vcc
	v_mul_lo_u32 v16, v16, s54
	v_add_u32_e32 v12, v16, v11
	v_add_u32_e32 v16, 8, v10
	v_lshrrev_b32_e32 v17, 7, v16
	v_and_b32_e32 v18, 0x7f, v16
	v_lshl_add_u32 v17, v17, 8, v18
	v_add_u32_e32 v17, s16, v17
	v_cndmask_b32_e32 v16, v17, v16, vcc
	v_mul_lo_u32 v16, v16, s54
	v_add_u32_e32 v13, v16, v11
	v_add_u32_e32 v16, 16, v10
	v_lshrrev_b32_e32 v17, 7, v16
	v_and_b32_e32 v18, 0x7f, v16
	v_lshl_add_u32 v17, v17, 8, v18
	v_add_u32_e32 v17, s16, v17
	v_cndmask_b32_e32 v16, v17, v16, vcc
	v_mul_lo_u32 v16, v16, s54
	v_add_u32_e32 v14, v16, v11
	v_add_u32_e32 v16, 24, v10
	v_lshrrev_b32_e32 v17, 7, v16
	v_and_b32_e32 v18, 0x7f, v16
	v_lshl_add_u32 v17, v17, 8, v18
	v_add_u32_e32 v17, s16, v17
	v_cndmask_b32_e32 v16, v17, v16, vcc
	v_mul_lo_u32 v16, v16, s54
	v_add_u32_e32 v15, v16, v11
	s_waitcnt vmcnt(0)
	ds_write_b32 v5, v20 offset:0
	ds_write_b32 v5, v21 offset:264
	ds_write_b32 v5, v22 offset:528
	ds_write_b32 v5, v23 offset:792
	ds_write_b32 v5, v24 offset:1056
	ds_write_b32 v5, v25 offset:1320
	ds_write_b32 v5, v26 offset:1584
	ds_write_b32 v5, v27 offset:1848
	ds_write_b32 v5, v28 offset:2112
	ds_write_b32 v5, v29 offset:2376
	ds_write_b32 v5, v30 offset:2640
	ds_write_b32 v5, v31 offset:2904
	s_waitcnt lgkmcnt(0)
; #define LAS __attribute__((address_space(3)))
; __device__ __forceinline__ unsigned pk2(float lo, float hi) { const f32x2 v = {lo, hi}; const bf16x2_t b = __builtin_convertvector(v, bf16x2_t); return __builtin_bit_cast(unsigned, b); }
; __device__ __forceinline__ int map13(int hidden, int which) { return (hidden >> 7) * 256 + which * 128 + (hidden & 127); }
; __device__ __forceinline__ void transpose_item(const float* W, int K, int N, const float* gain, bf16_t* WT, int mode, LAS float* scr, int item, int lane) {
;     ...
;     for (int i = 0; i < 32; ++i) { const int kk = 2 * i + (lane >> 5); float w = W[(size_t)(k0 + kk) * N + n0 + (lane & 31)]; if (gain) w *= gain[k0 + kk]; scr[kk * 33 + (lane & 31)] = w; }
;     asm volatile("s_waitcnt lgkmcnt(0)" ::: "memory");
;     const int c = lane & 7;
; #pragma unroll
;     for (int j = 0; j < 4; ++j) { const int n = (lane >> 3) + 8 * j; const LAS float* s = scr + (8 * c) * 33 + n;
;         u32x4 o; o.x = pk2(s[0 * 33], s[1 * 33]); o.y = pk2(s[2 * 33], s[3 * 33]); o.z = pk2(s[4 * 33], s[5 * 33]); o.w = pk2(s[6 * 33], s[7 * 33]);
;         const int row = (mode == 0) ? (n0 + n) : map13(n0 + n, mode - 1);
;         *(u32x4*)(WT + (size_t)row * K + k0 + 8 * c) = o; }
;     asm volatile("s_waitcnt lgkmcnt(0)" ::: "memory");
; __device__ __forceinline__ void phase0(const Ctx& C) {
;     ...
;     const float* x = C.in[0]; bf16_t* xb = (bf16_t*)(C.ws + WS_ACTA); float* ssq = (float*)(C.ws + WS_SSQA);
;     for (int row = gw; row < T_; row += 4 * NGW) {
;         f32x4 v[4][4];
; #pragma unroll
;         for (int r = 0; r < 4; ++r) { const int rw = (row + r * NGW < T_) ? row + r * NGW : row; const f32x4* xa = (const f32x4*)(x + (size_t)rw * D_) + lane;
	ds_write_b32 v5, v32 offset:3168
	ds_write_b32 v5, v33 offset:3432
	ds_write_b32 v5, v34 offset:3696
	ds_write_b32 v5, v35 offset:3960
	ds_write_b32 v5, v36 offset:4224
	ds_write_b32 v5, v37 offset:4488
	ds_write_b32 v5, v38 offset:4752
	ds_write_b32 v5, v39 offset:5016
	ds_write_b32 v5, v40 offset:5280
	ds_write_b32 v5, v41 offset:5544
	ds_write_b32 v5, v42 offset:5808
	ds_write_b32 v5, v43 offset:6072
	s_waitcnt lgkmcnt(0)
	ds_write_b32 v5, v44 offset:6336
	ds_write_b32 v5, v45 offset:6600
	ds_write_b32 v5, v46 offset:6864
	ds_write_b32 v5, v47 offset:7128
	ds_write_b32 v5, v48 offset:7392
	ds_write_b32 v5, v49 offset:7656
	ds_write_b32 v5, v50 offset:7920
	ds_write_b32 v5, v51 offset:8184
	s_waitcnt lgkmcnt(0)
	ds_read_b32 v60, v6 offset:0
	ds_read_b32 v61, v6 offset:132
	ds_read_b32 v62, v6 offset:264
	ds_read_b32 v63, v6 offset:396
	ds_read_b32 v64, v6 offset:528
	ds_read_b32 v65, v6 offset:660
	ds_read_b32 v66, v6 offset:792
	ds_read_b32 v67, v6 offset:924
	s_waitcnt lgkmcnt(0)
	ds_read_b32 v68, v6 offset:32
	ds_read_b32 v69, v6 offset:164
	ds_read_b32 v70, v6 offset:296
	ds_read_b32 v71, v6 offset:428
	ds_read_b32 v72, v6 offset:560
	ds_read_b32 v73, v6 offset:692
	ds_read_b32 v74, v6 offset:824
	ds_read_b32 v75, v6 offset:956
	v_mul_f32_e32 v60, v60, v52
	v_mul_f32_e32 v61, v61, v53
	v_mul_f32_e32 v62, v62, v54
	v_mul_f32_e32 v63, v63, v55
	v_mul_f32_e32 v64, v64, v56
	v_mul_f32_e32 v65, v65, v57
	v_mul_f32_e32 v66, v66, v58
	v_mul_f32_e32 v67, v67, v59
	v_cvt_pk_bf16_f32 v92, v60, v61
	v_cvt_pk_bf16_f32 v93, v62, v63
	v_cvt_pk_bf16_f32 v94, v64, v65
	v_cvt_pk_bf16_f32 v95, v66, v67
	global_store_dwordx4 v12, v[92:95], s[52:53]
	s_waitcnt lgkmcnt(0)
	ds_read_b32 v76, v6 offset:64
	ds_read_b32 v77, v6 offset:196
	ds_read_b32 v78, v6 offset:328
	ds_read_b32 v79, v6 offset:460
	ds_read_b32 v80, v6 offset:592
	ds_read_b32 v81, v6 offset:724
	ds_read_b32 v82, v6 offset:856
	ds_read_b32 v83, v6 offset:988
	v_mul_f32_e32 v68, v68, v52
	v_mul_f32_e32 v69, v69, v53
	v_mul_f32_e32 v70, v70, v54
	v_mul_f32_e32 v71, v71, v55
	v_mul_f32_e32 v72, v72, v56
	v_mul_f32_e32 v73, v73, v57
	v_mul_f32_e32 v74, v74, v58
	v_mul_f32_e32 v75, v75, v59
	v_cvt_pk_bf16_f32 v96, v68, v69
	v_cvt_pk_bf16_f32 v97, v70, v71
	v_cvt_pk_bf16_f32 v98, v72, v73
	v_cvt_pk_bf16_f32 v99, v74, v75
	global_store_dwordx4 v13, v[96:99], s[52:53]
	s_waitcnt lgkmcnt(0)
	ds_read_b32 v84, v6 offset:96
	ds_read_b32 v85, v6 offset:228
	ds_read_b32 v86, v6 offset:360
	ds_read_b32 v87, v6 offset:492
	ds_read_b32 v88, v6 offset:624
	ds_read_b32 v89, v6 offset:756
	ds_read_b32 v90, v6 offset:888
	ds_read_b32 v91, v6 offset:1020
	v_mul_f32_e32 v76, v76, v52
	v_mul_f32_e32 v77, v77, v53
	v_mul_f32_e32 v78, v78, v54
	v_mul_f32_e32 v79, v79, v55
	v_mul_f32_e32 v80, v80, v56
	v_mul_f32_e32 v81, v81, v57
	v_mul_f32_e32 v82, v82, v58
	v_mul_f32_e32 v83, v83, v59
	v_cvt_pk_bf16_f32 v20, v76, v77
	v_cvt_pk_bf16_f32 v21, v78, v79
	v_cvt_pk_bf16_f32 v22, v80, v81
	v_cvt_pk_bf16_f32 v23, v82, v83
	global_store_dwordx4 v14, v[20:23], s[52:53]
	s_waitcnt lgkmcnt(0)
	v_mul_f32_e32 v84, v84, v52
	v_mul_f32_e32 v85, v85, v53
	v_mul_f32_e32 v86, v86, v54
	v_mul_f32_e32 v87, v87, v55
	v_mul_f32_e32 v88, v88, v56
	v_mul_f32_e32 v89, v89, v57
	v_mul_f32_e32 v90, v90, v58
	v_mul_f32_e32 v91, v91, v59
	v_cvt_pk_bf16_f32 v24, v84, v85
	v_cvt_pk_bf16_f32 v25, v86, v87
	v_cvt_pk_bf16_f32 v26, v88, v89
	v_cvt_pk_bf16_f32 v27, v90, v91
	global_store_dwordx4 v15, v[24:27], s[52:53]
	s_add_i32 s2, s2, s3
	s_branch .Lmy_c0_loop
.Lmy_c0_exit:
.LBB0_153:
	s_cmpk_gt_i32 s10, 0x3fff
	s_cbranch_scc1 .LBB0_188
	v_lshlrev_b32_e32 v2, 4, v193
	v_mov_b32_e32 v3, 0
	v_readlane_b32 s2, v254, 22
	v_lshl_add_u64 v[50:51], s[36:37], 0, v[2:3]
	v_lshlrev_b32_e32 v2, 3, v193
	v_readlane_b32 s3, v254, 23
	v_cmp_gt_u32_e64 s[6:7], 16, v193
	v_cmp_eq_u32_e64 s[8:9], 0, v193
	v_lshl_add_u64 v[52:53], s[2:3], 0, v[2:3]
	v_readlane_b32 s2, v254, 24
	v_lshlrev_b32_e32 v2, 2, v193
	v_readlane_b32 s3, v254, 25
	s_lshl_b32 s1, s88, 4
	s_nop 0
	v_lshl_add_u64 v[54:55], s[2:3], 0, v[2:3]
	s_mul_i32 s2, s88, 24
	s_branch .LBB0_156

; __device__ __forceinline__ void convert_mid(const Ctx& C, int vbid, int vG) {
;     ...
;     const int gw = vbid * 8 + C.wave, NGW = vG * 8, lane = C.lane;
;     bf16_t* W2 = (bf16_t*)(C.ws + WS_W2A); bf16_t* Win = (bf16_t*)(C.ws + WS_WIN); bf16_t* Wout = (bf16_t*)(C.ws + WS_WOUT);
;     constexpr int I1 = 16 * 88, I2 = 44 * 32, IO = 16 * 32, NIT = I1 + I2 + IO;
;     for (int it = gw; it < NIT; it += NGW) {
;         int r = it;
;         if (r < I2) { transpose_item(C.in[5], FF_, D_, nullptr, W2, 0, scr, r, lane); continue; } r -= I2;
;         if (r < I1) { transpose_item(C.in[7], D_, FF_, C.in[6], Win, 0, scr, r, lane); continue; } r -= I1;
;         transpose_item(C.in[23], D_, D_, nullptr, Wout, 0, scr, r, lane);
;     }
; __global__ void __launch_bounds__(NTHR, 2) fwd_kernel(Args args) {
;     ...
;         { const int rem = S.nwg % C.G; __syncthreads(); if (rem == 0) convert_mid(C, C.bid, C.G); else if (C.bid >= rem) convert_mid(C, C.bid - rem, C.G - rem); }
.LBB0_259:
	s_abs_i32 s0, s88
	v_cvt_f32_u32_e32 v1, s0
	s_sub_i32 s1, 0, s0
	s_waitcnt lgkmcnt(0)
	s_barrier
	v_rcp_iflag_f32_e32 v1, v1
	s_nop 0
	v_mul_f32_e32 v1, 0x4f7ffffe, v1
	v_cvt_u32_f32_e32 v1, v1
	s_nop 0
	v_readfirstlane_b32 s2, v1
	s_mul_i32 s1, s1, s2
	s_mul_hi_u32 s1, s2, s1
	s_add_i32 s2, s2, s1
	s_mul_hi_u32 s1, s2, 0x580
	s_mul_i32 s1, s1, s0
	s_sub_i32 s1, 0x580, s1
	s_sub_i32 s2, s1, s0
	s_cmp_ge_u32 s1, s0
	s_cselect_b32 s1, s2, s1
	s_sub_i32 s2, s1, s0
	s_cmp_ge_u32 s1, s0
	s_cselect_b32 s1, s2, s1
	s_cmp_lg_u32 s1, 0
	s_cbranch_scc0 .LBB0_336
	s_cmp_lt_i32 s94, s1
	s_cbranch_scc1 .LBB0_338
	s_sub_i32 s0, s94, s1
	s_lshl_b32 s0, s0, 3
	s_add_i32 s0, s0, s80
	s_cmpk_gt_u32 s0, 0xcff
	s_cbranch_scc1 .LBB0_338
	s_waitcnt lgkmcnt(0)
	s_mov_b32 s2, s0
	s_sub_i32 s3, s88, s1
	s_lshl_b32 s3, s3, 3
	v_readlane_b32 s100, v254, 1
	v_readlane_b32 s101, v254, 2
	v_and_b32_e32 v1, 31, v193
	v_lshrrev_b32_e32 v2, 5, v193
	v_and_b32_e32 v3, 7, v193
	v_lshrrev_b32_e32 v4, 3, v193
	s_mul_i32 s16, s80, 0x2100
	v_mad_u32_u24 v5, v2, 33, v1
	v_lshl_add_u32 v5, v5, 2, s16
	v_mul_u32_u24_e32 v6, 0x108, v3
	v_add_u32_e32 v6, v6, v4
	v_lshl_add_u32 v6, v6, 2, s16
.Lmy_c1_loop:
	s_cmp_ge_i32 s2, 0xd00
	s_cbranch_scc1 .Lmy_c1_exit
	s_cmp_ge_i32 s2, 0x580
	s_cbranch_scc1 .Lmy_c1_seg1
	s_mov_b32 s15, s2
	s_mov_b32 s16, 0x8000001
	s_mul_hi_u32 s14, s15, s16
	s_mul_i32 s16, s14, 32
	s_sub_i32 s15, s15, s16
	s_load_dwordx2 s[4:5], s[100:101], 0x28
	s_mov_b64 s[18:19], 0
	s_add_u32 s52, s26, 0xa300000
	s_addc_u32 s53, s27, 0
	s_mov_b32 s6, 0x1000
	s_mov_b32 s54, 0x1600
	s_mov_b32 s56, 0
	s_waitcnt lgkmcnt(0)
	s_branch .Lmy_c1_item
.Lmy_c1_seg1:
	s_cmp_ge_i32 s2, 0xb00
	s_cbranch_scc1 .Lmy_c1_seg2
	s_sub_i32 s15, s2, 0x580
	s_mov_b32 s16, 0x2e8ba2f
	s_mul_hi_u32 s14, s15, s16
	s_mul_i32 s16, s14, 88
	s_sub_i32 s15, s15, s16
	s_load_dwordx2 s[4:5], s[100:101], 0x38
	s_load_dwordx2 s[18:19], s[100:101], 0x30
	s_add_u32 s52, s26, 0xa880000
	s_addc_u32 s53, s27, 0
	s_mov_b32 s6, 0x2c00
	s_mov_b32 s54, 0x800
	s_mov_b32 s56, 0
	s_waitcnt lgkmcnt(0)
	s_branch .Lmy_c1_item
.Lmy_c1_seg2:
	s_sub_i32 s15, s2, 0xb00
	s_mov_b32 s16, 0x8000001
	s_mul_hi_u32 s14, s15, s16
	s_mul_i32 s16, s14, 32
	s_sub_i32 s15, s15, s16
	s_load_dwordx2 s[4:5], s[100:101], 0xb8
	s_mov_b64 s[18:19], 0
	s_add_u32 s52, s26, 0xfc00000
	s_addc_u32 s53, s27, 0
	s_mov_b32 s6, 0x1000
	s_mov_b32 s54, 0x800
	s_mov_b32 s56, 0
	s_waitcnt lgkmcnt(0)

; #define LAS __attribute__((address_space(3)))
; __device__ __forceinline__ void convert_w13b(const Ctx& C) {
;     LAS float* scr = (LAS float*)(C.lds + C.wave * 8448);
;     const int gw = C.bid * 8 + C.wave, NGW = C.G * 8, lane = C.lane;
;     bf16_t* W13 = (bf16_t*)(C.ws + WS_W13B);
;     constexpr int I1 = 16 * 88;
;     for (int it = gw; it < 2 * I1; it += NGW) {
;         if (it < I1) transpose_item(C.in[25], D_, FF_, C.in[24], W13, 1, scr, it, lane);
;         else transpose_item(C.in[26], D_, FF_, C.in[24], W13, 2, scr, it - I1, lane);
;     }
.LBB0_1122:
	v_readlane_b32 s0, v254, 1
	v_readlane_b32 s1, v254, 2
	s_load_dwordx16 s[8:23], s[0:1], 0xc0
	s_cmp_lt_i32 s76, 9
	s_cselect_b64 s[0:1], -1, 0
	s_and_b64 s[44:45], s[0:1], s[6:7]
	s_andn2_b64 vcc, exec, s[44:45]
	s_cbranch_vccnz .LBB0_1298
	s_waitcnt lgkmcnt(0)
	s_lshl_b32 s2, s94, 3
	s_add_i32 s2, s80, s2
	s_lshl_b32 s3, s88, 3
	v_readlane_b32 s100, v254, 1
	v_readlane_b32 s101, v254, 2
	v_and_b32_e32 v1, 31, v193
	v_lshrrev_b32_e32 v2, 5, v193
	v_and_b32_e32 v3, 7, v193
	v_lshrrev_b32_e32 v4, 3, v193
	s_mul_i32 s30, s80, 0x2100
	v_mad_u32_u24 v5, v2, 33, v1
	v_lshl_add_u32 v5, v5, 2, s30
	v_mul_u32_u24_e32 v6, 0x108, v3
	v_add_u32_e32 v6, v6, v4
	v_lshl_add_u32 v6, v6, 2, s30
.Lmy_c8_loop:
	s_cmp_ge_i32 s2, 0xb00
	s_cbranch_scc1 .Lmy_c8_exit
	s_cmp_ge_i32 s2, 0x580
	s_cbranch_scc1 .Lmy_c8_seg1
	s_mov_b32 s29, s2
	s_mov_b32 s30, 0x2e8ba2f
	s_mul_hi_u32 s28, s29, s30
	s_mul_i32 s30, s28, 88
	s_sub_i32 s29, s29, s30
	s_load_dwordx2 s[4:5], s[100:101], 0xc8
	s_load_dwordx2 s[34:35], s[100:101], 0xc0
	s_add_u32 s10, s26, 0x9800000
	s_addc_u32 s11, s27, 0
	s_mov_b32 s6, 0x2c00
	s_mov_b32 s12, 0x800
	s_mov_b32 s13, 1
	s_waitcnt lgkmcnt(0)
	s_branch .Lmy_c8_item
.Lmy_c8_seg1:
	s_sub_i32 s29, s2, 0x580
	s_mov_b32 s30, 0x2e8ba2f
	s_mul_hi_u32 s28, s29, s30
	s_mul_i32 s30, s28, 88
	s_sub_i32 s29, s29, s30
	s_load_dwordx2 s[4:5], s[100:101], 0xd0
	s_load_dwordx2 s[34:35], s[100:101], 0xc0
	s_add_u32 s10, s26, 0x9800000
	s_addc_u32 s11, s27, 0
	s_mov_b32 s6, 0x2c00
	s_mov_b32 s12, 0x800
	s_mov_b32 s13, 2
	s_waitcnt lgkmcnt(0)
.Lmy_c8_item:
	s_lshl_b32 s28, s28, 6
	s_lshl_b32 s29, s29, 5
	v_mul_lo_u32 v7, v2, s6
	v_lshl_add_u32 v7, v1, 2, v7
	s_cmp_eq_u64 s[34:35], 0
	s_cbranch_scc1 .Lmy_c8_nog
	v_lshlrev_b32_e32 v9, 3, v3
	v_add_lshl_u32 v9, v9, s28, 2
	global_load_dwordx4 v[52:55], v9, s[34:35]
	global_load_dwordx4 v[56:59], v9, s[34:35] offset:16
	s_branch .Lmy_c8_g

; #define LAS __attribute__((address_space(3)))
; __device__ __forceinline__ unsigned pk2(float lo, float hi) { const f32x2 v = {lo, hi}; const bf16x2_t b = __builtin_convertvector(v, bf16x2_t); return __builtin_bit_cast(unsigned, b); }
; __device__ __forceinline__ int map13(int hidden, int which) { return (hidden >> 7) * 256 + which * 128 + (hidden & 127); }
; __device__ __forceinline__ void transpose_item(const float* W, int K, int N, const float* gain, bf16_t* WT, int mode, LAS float* scr, int item, int lane) {
;     const int nblk = N / 32, kb = item / nblk, nb = item % nblk, k0 = 64 * kb, n0 = 32 * nb;
; #pragma unroll
;     for (int i = 0; i < 32; ++i) { const int kk = 2 * i + (lane >> 5); float w = W[(size_t)(k0 + kk) * N + n0 + (lane & 31)]; if (gain) w *= gain[k0 + kk]; scr[kk * 33 + (lane & 31)] = w; }
;     asm volatile("s_waitcnt lgkmcnt(0)" ::: "memory");
;     const int c = lane & 7;
; #pragma unroll
;     for (int j = 0; j < 4; ++j) { const int n = (lane >> 3) + 8 * j; const LAS float* s = scr + (8 * c) * 33 + n;
;         u32x4 o; o.x = pk2(s[0 * 33], s[1 * 33]); o.y = pk2(s[2 * 33], s[3 * 33]); o.z = pk2(s[4 * 33], s[5 * 33]); o.w = pk2(s[6 * 33], s[7 * 33]);
;         const int row = (mode == 0) ? (n0 + n) : map13(n0 + n, mode - 1);
;         *(u32x4*)(WT + (size_t)row * K + k0 + 8 * c) = o; }
.Lmy_c8_g:
	s_mul_i32 s34, s28, s6
	s_mul_hi_u32 s35, s28, s6
	s_lshl_b32 s30, s29, 2
	s_add_u32 s34, s34, s30
	s_addc_u32 s35, s35, 0
	s_add_u32 s34, s34, s4
	s_addc_u32 s35, s35, s5
	s_lshl_b32 s30, s6, 1
	global_load_dword v20, v7, s[34:35]
	s_add_u32 s34, s34, s30
	s_addc_u32 s35, s35, 0
	global_load_dword v21, v7, s[34:35]
	s_add_u32 s34, s34, s30
	s_addc_u32 s35, s35, 0
	global_load_dword v22, v7, s[34:35]
	s_add_u32 s34, s34, s30
	s_addc_u32 s35, s35, 0
	global_load_dword v23, v7, s[34:35]
	s_add_u32 s34, s34, s30
	s_addc_u32 s35, s35, 0
	global_load_dword v24, v7, s[34:35]
	s_add_u32 s34, s34, s30
	s_addc_u32 s35, s35, 0
	global_load_dword v25, v7, s[34:35]
	s_add_u32 s34, s34, s30
	s_addc_u32 s35, s35, 0
	global_load_dword v26, v7, s[34:35]
	s_add_u32 s34, s34, s30
	s_addc_u32 s35, s35, 0
	global_load_dword v27, v7, s[34:35]
	s_add_u32 s34, s34, s30
	s_addc_u32 s35, s35, 0
	global_load_dword v28, v7, s[34:35]
	s_add_u32 s34, s34, s30
	s_addc_u32 s35, s35, 0
	global_load_dword v29, v7, s[34:35]
	s_add_u32 s34, s34, s30
	s_addc_u32 s35, s35, 0
	global_load_dword v30, v7, s[34:35]
	s_add_u32 s34, s34, s30
	s_addc_u32 s35, s35, 0
	global_load_dword v31, v7, s[34:35]
	s_add_u32 s34, s34, s30
	s_addc_u32 s35, s35, 0
	global_load_dword v32, v7, s[34:35]
	s_add_u32 s34, s34, s30
	s_addc_u32 s35, s35, 0
	global_load_dword v33, v7, s[34:35]
	s_add_u32 s34, s34, s30
	s_addc_u32 s35, s35, 0
	global_load_dword v34, v7, s[34:35]
	s_add_u32 s34, s34, s30
	s_addc_u32 s35, s35, 0
	global_load_dword v35, v7, s[34:35]
	s_add_u32 s34, s34, s30
	s_addc_u32 s35, s35, 0
	global_load_dword v36, v7, s[34:35]
	s_add_u32 s34, s34, s30
	s_addc_u32 s35, s35, 0
	global_load_dword v37, v7, s[34:35]
	s_add_u32 s34, s34, s30
	s_addc_u32 s35, s35, 0
	global_load_dword v38, v7, s[34:35]
	s_add_u32 s34, s34, s30
	s_addc_u32 s35, s35, 0
	global_load_dword v39, v7, s[34:35]
	s_add_u32 s34, s34, s30
	s_addc_u32 s35, s35, 0
	global_load_dword v40, v7, s[34:35]
	s_add_u32 s34, s34, s30
	s_addc_u32 s35, s35, 0
	global_load_dword v41, v7, s[34:35]
	s_add_u32 s34, s34, s30
	s_addc_u32 s35, s35, 0
	global_load_dword v42, v7, s[34:35]
	s_add_u32 s34, s34, s30
	s_addc_u32 s35, s35, 0
	global_load_dword v43, v7, s[34:35]
	s_add_u32 s34, s34, s30
	s_addc_u32 s35, s35, 0
	global_load_dword v44, v7, s[34:35]
	s_add_u32 s34, s34, s30
	s_addc_u32 s35, s35, 0
	global_load_dword v45, v7, s[34:35]
	s_add_u32 s34, s34, s30
	s_addc_u32 s35, s35, 0
	global_load_dword v46, v7, s[34:35]
	s_add_u32 s34, s34, s30
	s_addc_u32 s35, s35, 0
	global_load_dword v47, v7, s[34:35]
	s_add_u32 s34, s34, s30
	s_addc_u32 s35, s35, 0
	global_load_dword v48, v7, s[34:35]
	s_add_u32 s34, s34, s30
	s_addc_u32 s35, s35, 0
	global_load_dword v49, v7, s[34:35]
	s_add_u32 s34, s34, s30
	s_addc_u32 s35, s35, 0
	global_load_dword v50, v7, s[34:35]
	s_add_u32 s34, s34, s30
	s_addc_u32 s35, s35, 0
	global_load_dword v51, v7, s[34:35]
	v_add_u32_e32 v10, s29, v4
	s_cmp_eq_u32 s13, 0
	s_cselect_b64 vcc, -1, 0
	s_add_i32 s30, s13, -1
	s_lshl_b32 s30, s30, 7
	v_lshlrev_b32_e32 v11, 3, v3
	v_add_lshl_u32 v11, v11, s28, 1
	v_add_u32_e32 v16, 0, v10
	v_lshrrev_b32_e32 v17, 7, v16
	v_and_b32_e32 v18, 0x7f, v16
	v_lshl_add_u32 v17, v17, 8, v18
	v_add_u32_e32 v17, s30, v17
	v_cndmask_b32_e32 v16, v17, v16, vcc
	v_mul_lo_u32 v16, v16, s12
	v_add_u32_e32 v12, v16, v11
	v_add_u32_e32 v16, 8, v10
	v_lshrrev_b32_e32 v17, 7, v16
	v_and_b32_e32 v18, 0x7f, v16
	v_lshl_add_u32 v17, v17, 8, v18
	v_add_u32_e32 v17, s30, v17
	v_cndmask_b32_e32 v16, v17, v16, vcc
	v_mul_lo_u32 v16, v16, s12
	v_add_u32_e32 v13, v16, v11
	v_add_u32_e32 v16, 16, v10
	v_lshrrev_b32_e32 v17, 7, v16
	v_and_b32_e32 v18, 0x7f, v16
	v_lshl_add_u32 v17, v17, 8, v18
	v_add_u32_e32 v17, s30, v17
	v_cndmask_b32_e32 v16, v17, v16, vcc
	v_mul_lo_u32 v16, v16, s12
	v_add_u32_e32 v14, v16, v11
	v_add_u32_e32 v16, 24, v10
	v_lshrrev_b32_e32 v17, 7, v16
	v_and_b32_e32 v18, 0x7f, v16
	v_lshl_add_u32 v17, v17, 8, v18
	v_add_u32_e32 v17, s30, v17
	v_cndmask_b32_e32 v16, v17, v16, vcc
	v_mul_lo_u32 v16, v16, s12
	v_add_u32_e32 v15, v16, v11
	s_waitcnt vmcnt(0)
; #define LAS __attribute__((address_space(3)))
; __device__ __forceinline__ unsigned pk2(float lo, float hi) { const f32x2 v = {lo, hi}; const bf16x2_t b = __builtin_convertvector(v, bf16x2_t); return __builtin_bit_cast(unsigned, b); }
; __device__ __forceinline__ int map13(int hidden, int which) { return (hidden >> 7) * 256 + which * 128 + (hidden & 127); }
; __device__ __forceinline__ void transpose_item(const float* W, int K, int N, const float* gain, bf16_t* WT, int mode, LAS float* scr, int item, int lane) {
;     ...
;     for (int i = 0; i < 32; ++i) { const int kk = 2 * i + (lane >> 5); float w = W[(size_t)(k0 + kk) * N + n0 + (lane & 31)]; if (gain) w *= gain[k0 + kk]; scr[kk * 33 + (lane & 31)] = w; }
;     asm volatile("s_waitcnt lgkmcnt(0)" ::: "memory");
;     const int c = lane & 7;
; #pragma unroll
;     for (int j = 0; j < 4; ++j) { const int n = (lane >> 3) + 8 * j; const LAS float* s = scr + (8 * c) * 33 + n;
;         u32x4 o; o.x = pk2(s[0 * 33], s[1 * 33]); o.y = pk2(s[2 * 33], s[3 * 33]); o.z = pk2(s[4 * 33], s[5 * 33]); o.w = pk2(s[6 * 33], s[7 * 33]);
;         const int row = (mode == 0) ? (n0 + n) : map13(n0 + n, mode - 1);
;         *(u32x4*)(WT + (size_t)row * K + k0 + 8 * c) = o; }
;     asm volatile("s_waitcnt lgkmcnt(0)" ::: "memory");
	ds_write_b32 v5, v20 offset:0
	ds_write_b32 v5, v21 offset:264
	ds_write_b32 v5, v22 offset:528
	ds_write_b32 v5, v23 offset:792
	ds_write_b32 v5, v24 offset:1056
	ds_write_b32 v5, v25 offset:1320
	ds_write_b32 v5, v26 offset:1584
	ds_write_b32 v5, v27 offset:1848
	ds_write_b32 v5, v28 offset:2112
	ds_write_b32 v5, v29 offset:2376
	ds_write_b32 v5, v30 offset:2640
	ds_write_b32 v5, v31 offset:2904
	s_waitcnt lgkmcnt(0)
	ds_write_b32 v5, v32 offset:3168
	ds_write_b32 v5, v33 offset:3432
	ds_write_b32 v5, v34 offset:3696
	ds_write_b32 v5, v35 offset:3960
	ds_write_b32 v5, v36 offset:4224
	ds_write_b32 v5, v37 offset:4488
	ds_write_b32 v5, v38 offset:4752
	ds_write_b32 v5, v39 offset:5016
	ds_write_b32 v5, v40 offset:5280
	ds_write_b32 v5, v41 offset:5544
	ds_write_b32 v5, v42 offset:5808
	ds_write_b32 v5, v43 offset:6072
	s_waitcnt lgkmcnt(0)
	ds_write_b32 v5, v44 offset:6336
	ds_write_b32 v5, v45 offset:6600
	ds_write_b32 v5, v46 offset:6864
	ds_write_b32 v5, v47 offset:7128
	ds_write_b32 v5, v48 offset:7392
	ds_write_b32 v5, v49 offset:7656
	ds_write_b32 v5, v50 offset:7920
	ds_write_b32 v5, v51 offset:8184
	s_waitcnt lgkmcnt(0)
	ds_read_b32 v60, v6 offset:0
	ds_read_b32 v61, v6 offset:132
	ds_read_b32 v62, v6 offset:264
	ds_read_b32 v63, v6 offset:396
	ds_read_b32 v64, v6 offset:528
	ds_read_b32 v65, v6 offset:660
	ds_read_b32 v66, v6 offset:792
	ds_read_b32 v67, v6 offset:924
	s_waitcnt lgkmcnt(0)
	ds_read_b32 v68, v6 offset:32
	ds_read_b32 v69, v6 offset:164
	ds_read_b32 v70, v6 offset:296
	ds_read_b32 v71, v6 offset:428
	ds_read_b32 v72, v6 offset:560
	ds_read_b32 v73, v6 offset:692
	ds_read_b32 v74, v6 offset:824
	ds_read_b32 v75, v6 offset:956
	v_mul_f32_e32 v60, v60, v52
	v_mul_f32_e32 v61, v61, v53
	v_mul_f32_e32 v62, v62, v54
	v_mul_f32_e32 v63, v63, v55
	v_mul_f32_e32 v64, v64, v56
	v_mul_f32_e32 v65, v65, v57
	v_mul_f32_e32 v66, v66, v58
	v_mul_f32_e32 v67, v67, v59
	v_cvt_pk_bf16_f32 v92, v60, v61
	v_cvt_pk_bf16_f32 v93, v62, v63
	v_cvt_pk_bf16_f32 v94, v64, v65
	v_cvt_pk_bf16_f32 v95, v66, v67
	global_store_dwordx4 v12, v[92:95], s[10:11]
	s_waitcnt lgkmcnt(0)
	ds_read_b32 v76, v6 offset:64
	ds_read_b32 v77, v6 offset:196
	ds_read_b32 v78, v6 offset:328
	ds_read_b32 v79, v6 offset:460
	ds_read_b32 v80, v6 offset:592
	ds_read_b32 v81, v6 offset:724
	ds_read_b32 v82, v6 offset:856
	ds_read_b32 v83, v6 offset:988
	v_mul_f32_e32 v68, v68, v52
	v_mul_f32_e32 v69, v69, v53
	v_mul_f32_e32 v70, v70, v54
	v_mul_f32_e32 v71, v71, v55
	v_mul_f32_e32 v72, v72, v56
	v_mul_f32_e32 v73, v73, v57
	v_mul_f32_e32 v74, v74, v58
	v_mul_f32_e32 v75, v75, v59
	v_cvt_pk_bf16_f32 v96, v68, v69
	v_cvt_pk_bf16_f32 v97, v70, v71
	v_cvt_pk_bf16_f32 v98, v72, v73
	v_cvt_pk_bf16_f32 v99, v74, v75
	global_store_dwordx4 v13, v[96:99], s[10:11]
	s_waitcnt lgkmcnt(0)
	ds_read_b32 v84, v6 offset:96
	ds_read_b32 v85, v6 offset:228
	ds_read_b32 v86, v6 offset:360
	ds_read_b32 v87, v6 offset:492
	ds_read_b32 v88, v6 offset:624
	ds_read_b32 v89, v6 offset:756
	ds_read_b32 v90, v6 offset:888
	ds_read_b32 v91, v6 offset:1020
	v_mul_f32_e32 v76, v76, v52
	v_mul_f32_e32 v77, v77, v53
	v_mul_f32_e32 v78, v78, v54
	v_mul_f32_e32 v79, v79, v55
	v_mul_f32_e32 v80, v80, v56
	v_mul_f32_e32 v81, v81, v57
	v_mul_f32_e32 v82, v82, v58
	v_mul_f32_e32 v83, v83, v59
	v_cvt_pk_bf16_f32 v20, v76, v77
	v_cvt_pk_bf16_f32 v21, v78, v79
	v_cvt_pk_bf16_f32 v22, v80, v81
	v_cvt_pk_bf16_f32 v23, v82, v83
	global_store_dwordx4 v14, v[20:23], s[10:11]
	s_waitcnt lgkmcnt(0)
	v_mul_f32_e32 v84, v84, v52
	v_mul_f32_e32 v85, v85, v53
	v_mul_f32_e32 v86, v86, v54
	v_mul_f32_e32 v87, v87, v55
	v_mul_f32_e32 v88, v88, v56
	v_mul_f32_e32 v89, v89, v57
	v_mul_f32_e32 v90, v90, v58
	v_mul_f32_e32 v91, v91, v59
	v_cvt_pk_bf16_f32 v24, v84, v85
	v_cvt_pk_bf16_f32 v25, v86, v87
	v_cvt_pk_bf16_f32 v26, v88, v89
	v_cvt_pk_bf16_f32 v27, v90, v91
	global_store_dwordx4 v15, v[24:27], s[10:11]
	s_add_i32 s2, s2, s3
	s_branch .Lmy_c8_loop

; #define LAS __attribute__((address_space(3)))
; __device__ __forceinline__ void convert_late(const Ctx& C, int vbid, int vG) {
;     LAS float* scr = (LAS float*)(C.lds + C.wave * 8448);
;     const int gw = vbid * 8 + C.wave, NGW = vG * 8, lane = C.lane;
;     bf16_t* W2 = (bf16_t*)(C.ws + WS_W2B); bf16_t* Wg = (bf16_t*)(C.ws + WS_WG); bf16_t* Wple = (bf16_t*)(C.ws + WS_WPLE);
;     constexpr int I2 = 44 * 32, IG = 16 * 32, IP = 4 * 32, NIT = I2 + IG + IP;
;     for (int it = gw; it < NIT; it += NGW) {
;         int r = it;
;         if (r < I2) { transpose_item(C.in[27], FF_, D_, nullptr, W2, 0, scr, r, lane); continue; } r -= I2;
;         if (r < IG) { transpose_item(C.in[29], D_, D_, C.in[28], Wg, 0, scr, r, lane); continue; } r -= IG;
;         transpose_item(C.in[30], 256, D_, nullptr, Wple, 0, scr, r, lane);
;     }
; __global__ void __launch_bounds__(NTHR, 2) fwd_kernel(Args args) {
;     ...
;         { const int rem = S.nwg % C.G; __syncthreads(); if (rem == 0) convert_late(C, C.bid, C.G); else if (C.bid >= rem) convert_late(C, C.bid - rem, C.G - rem); }
.LBB0_1369:
	s_abs_i32 s0, s88
	v_cvt_f32_u32_e32 v1, s0
	s_sub_i32 s1, 0, s0
	s_barrier
	v_rcp_iflag_f32_e32 v1, v1
	s_nop 0
	v_mul_f32_e32 v1, 0x4f7ffffe, v1
	v_cvt_u32_f32_e32 v1, v1
	s_nop 0
	v_readfirstlane_b32 s2, v1
	s_mul_i32 s1, s1, s2
	s_mul_hi_u32 s1, s2, s1
	s_add_i32 s2, s2, s1
	s_mul_hi_u32 s1, s2, 0x580
	s_mul_i32 s1, s1, s0
	s_sub_i32 s1, 0x580, s1
	s_sub_i32 s2, s1, s0
	s_cmp_ge_u32 s1, s0
	s_cselect_b32 s1, s2, s1
	s_sub_i32 s2, s1, s0
	s_cmp_ge_u32 s1, s0
	s_cselect_b32 s0, s2, s1
	s_cmp_lg_u32 s0, 0
	s_cbranch_scc0 .LBB0_1448
	s_cmp_lt_i32 s94, s0
	s_cbranch_scc1 .LBB0_1452
	s_sub_i32 s1, s94, s0
	s_sub_i32 s0, s88, s0
	s_lshl_b32 s1, s1, 3
	s_add_i32 s6, s1, s80
	s_lshl_b32 s10, s0, 3
	s_cmpk_gt_u32 s6, 0x7ff
	s_cbranch_scc1 .LBB0_1449
	s_waitcnt lgkmcnt(0)
	s_mov_b32 s7, s6
	s_mov_b32 s11, s10
	v_readlane_b32 s100, v254, 1
	v_readlane_b32 s101, v254, 2
	v_and_b32_e32 v1, 31, v193
	v_lshrrev_b32_e32 v2, 5, v193
	v_and_b32_e32 v3, 7, v193
	v_lshrrev_b32_e32 v4, 3, v193
	s_mul_i32 s43, s80, 0x2100
	v_mad_u32_u24 v5, v2, 33, v1
	v_lshl_add_u32 v5, v5, 2, s43
	v_mul_u32_u24_e32 v6, 0x108, v3
	v_add_u32_e32 v6, v6, v4
	v_lshl_add_u32 v6, v6, 2, s43
.Lmy_c9_loop:
	s_cmp_ge_i32 s7, 0x800
	s_cbranch_scc1 .Lmy_c9_exit
	s_cmp_ge_i32 s7, 0x580
	s_cbranch_scc1 .Lmy_c9_seg1
	s_mov_b32 s42, s7
	s_mov_b32 s43, 0x8000001
	s_mul_hi_u32 s29, s42, s43
	s_mul_i32 s43, s29, 32
	s_sub_i32 s42, s42, s43
	s_load_dwordx2 s[0:1], s[100:101], 0xd8
	s_mov_b64 s[2:3], 0
	s_add_u32 s4, s26, 0xa300000
	s_addc_u32 s5, s27, 0
	s_mov_b32 s12, 0x1000
	s_mov_b32 s13, 0x1600
	s_mov_b32 s28, 0
	s_waitcnt lgkmcnt(0)
	s_branch .Lmy_c9_item
.Lmy_c9_seg1:
	s_cmp_ge_i32 s7, 0x780
	s_cbranch_scc1 .Lmy_c9_seg2
	s_sub_i32 s42, s7, 0x580
	s_mov_b32 s43, 0x8000001
	s_mul_hi_u32 s29, s42, s43
	s_mul_i32 s43, s29, 32
	s_sub_i32 s42, s42, s43
	s_load_dwordx2 s[0:1], s[100:101], 0xe8
	s_load_dwordx2 s[2:3], s[100:101], 0xe0
	s_add_u32 s4, s26, 0xa880000
	s_addc_u32 s5, s27, 0
	s_mov_b32 s12, 0x1000
	s_mov_b32 s13, 0x800
	s_mov_b32 s28, 0
	s_waitcnt lgkmcnt(0)
	s_branch .Lmy_c9_item
.Lmy_c9_seg2:
	s_sub_i32 s42, s7, 0x780
	s_mov_b32 s43, 0x8000001
	s_mul_hi_u32 s29, s42, s43
	s_mul_i32 s43, s29, 32
	s_sub_i32 s42, s42, s43
	s_load_dwordx2 s[0:1], s[100:101], 0xf0
	s_mov_b64 s[2:3], 0
	s_add_u32 s4, s26, 0xab00000
	s_addc_u32 s5, s27, 0
	s_mov_b32 s12, 0x1000
	s_mov_b32 s13, 0x200
	s_mov_b32 s28, 0
	s_waitcnt lgkmcnt(0)
.Lmy_c9_item:
	s_lshl_b32 s29, s29, 6
	s_lshl_b32 s42, s42, 5
	v_mul_lo_u32 v7, v2, s12
	v_lshl_add_u32 v7, v1, 2, v7
	s_cmp_eq_u64 s[2:3], 0
	s_cbranch_scc1 .Lmy_c9_nog
	v_lshlrev_b32_e32 v9, 3, v3
	v_add_lshl_u32 v9, v9, s29, 2
	global_load_dwordx4 v[52:55], v9, s[2:3]
	global_load_dwordx4 v[56:59], v9, s[2:3] offset:16
	s_branch .Lmy_c9_g

; #define LAS __attribute__((address_space(3)))
; __device__ __forceinline__ unsigned pk2(float lo, float hi) { const f32x2 v = {lo, hi}; const bf16x2_t b = __builtin_convertvector(v, bf16x2_t); return __builtin_bit_cast(unsigned, b); }
; __device__ __forceinline__ int map13(int hidden, int which) { return (hidden >> 7) * 256 + which * 128 + (hidden & 127); }
; __device__ __forceinline__ void transpose_item(const float* W, int K, int N, const float* gain, bf16_t* WT, int mode, LAS float* scr, int item, int lane) {
;     const int nblk = N / 32, kb = item / nblk, nb = item % nblk, k0 = 64 * kb, n0 = 32 * nb;
; #pragma unroll
;     for (int i = 0; i < 32; ++i) { const int kk = 2 * i + (lane >> 5); float w = W[(size_t)(k0 + kk) * N + n0 + (lane & 31)]; if (gain) w *= gain[k0 + kk]; scr[kk * 33 + (lane & 31)] = w; }
;     asm volatile("s_waitcnt lgkmcnt(0)" ::: "memory");
;     const int c = lane & 7;
; #pragma unroll
;     for (int j = 0; j < 4; ++j) { const int n = (lane >> 3) + 8 * j; const LAS float* s = scr + (8 * c) * 33 + n;
;         u32x4 o; o.x = pk2(s[0 * 33], s[1 * 33]); o.y = pk2(s[2 * 33], s[3 * 33]); o.z = pk2(s[4 * 33], s[5 * 33]); o.w = pk2(s[6 * 33], s[7 * 33]);
;         const int row = (mode == 0) ? (n0 + n) : map13(n0 + n, mode - 1);
;         *(u32x4*)(WT + (size_t)row * K + k0 + 8 * c) = o; }
.Lmy_c9_g:
	s_mul_i32 s2, s29, s12
	s_mul_hi_u32 s3, s29, s12
	s_lshl_b32 s43, s42, 2
	s_add_u32 s2, s2, s43
	s_addc_u32 s3, s3, 0
	s_add_u32 s2, s2, s0
	s_addc_u32 s3, s3, s1
	s_lshl_b32 s43, s12, 1
	global_load_dword v20, v7, s[2:3]
	s_add_u32 s2, s2, s43
	s_addc_u32 s3, s3, 0
	global_load_dword v21, v7, s[2:3]
	s_add_u32 s2, s2, s43
	s_addc_u32 s3, s3, 0
	global_load_dword v22, v7, s[2:3]
	s_add_u32 s2, s2, s43
	s_addc_u32 s3, s3, 0
	global_load_dword v23, v7, s[2:3]
	s_add_u32 s2, s2, s43
	s_addc_u32 s3, s3, 0
	global_load_dword v24, v7, s[2:3]
	s_add_u32 s2, s2, s43
	s_addc_u32 s3, s3, 0
	global_load_dword v25, v7, s[2:3]
	s_add_u32 s2, s2, s43
	s_addc_u32 s3, s3, 0
	global_load_dword v26, v7, s[2:3]
	s_add_u32 s2, s2, s43
	s_addc_u32 s3, s3, 0
	global_load_dword v27, v7, s[2:3]
	s_add_u32 s2, s2, s43
	s_addc_u32 s3, s3, 0
	global_load_dword v28, v7, s[2:3]
	s_add_u32 s2, s2, s43
	s_addc_u32 s3, s3, 0
	global_load_dword v29, v7, s[2:3]
	s_add_u32 s2, s2, s43
	s_addc_u32 s3, s3, 0
	global_load_dword v30, v7, s[2:3]
	s_add_u32 s2, s2, s43
	s_addc_u32 s3, s3, 0
	global_load_dword v31, v7, s[2:3]
	s_add_u32 s2, s2, s43
	s_addc_u32 s3, s3, 0
	global_load_dword v32, v7, s[2:3]
	s_add_u32 s2, s2, s43
	s_addc_u32 s3, s3, 0
	global_load_dword v33, v7, s[2:3]
	s_add_u32 s2, s2, s43
	s_addc_u32 s3, s3, 0
	global_load_dword v34, v7, s[2:3]
	s_add_u32 s2, s2, s43
	s_addc_u32 s3, s3, 0
	global_load_dword v35, v7, s[2:3]
	s_add_u32 s2, s2, s43
	s_addc_u32 s3, s3, 0
	global_load_dword v36, v7, s[2:3]
	s_add_u32 s2, s2, s43
	s_addc_u32 s3, s3, 0
	global_load_dword v37, v7, s[2:3]
	s_add_u32 s2, s2, s43
	s_addc_u32 s3, s3, 0
	global_load_dword v38, v7, s[2:3]
	s_add_u32 s2, s2, s43
	s_addc_u32 s3, s3, 0
	global_load_dword v39, v7, s[2:3]
	s_add_u32 s2, s2, s43
	s_addc_u32 s3, s3, 0
	global_load_dword v40, v7, s[2:3]
	s_add_u32 s2, s2, s43
	s_addc_u32 s3, s3, 0
	global_load_dword v41, v7, s[2:3]
	s_add_u32 s2, s2, s43
	s_addc_u32 s3, s3, 0
	global_load_dword v42, v7, s[2:3]
	s_add_u32 s2, s2, s43
	s_addc_u32 s3, s3, 0
	global_load_dword v43, v7, s[2:3]
	s_add_u32 s2, s2, s43
	s_addc_u32 s3, s3, 0
	global_load_dword v44, v7, s[2:3]
	s_add_u32 s2, s2, s43
	s_addc_u32 s3, s3, 0
	global_load_dword v45, v7, s[2:3]
	s_add_u32 s2, s2, s43
	s_addc_u32 s3, s3, 0
	global_load_dword v46, v7, s[2:3]
	s_add_u32 s2, s2, s43
	s_addc_u32 s3, s3, 0
	global_load_dword v47, v7, s[2:3]
	s_add_u32 s2, s2, s43
	s_addc_u32 s3, s3, 0
	global_load_dword v48, v7, s[2:3]
	s_add_u32 s2, s2, s43
	s_addc_u32 s3, s3, 0
	global_load_dword v49, v7, s[2:3]
	s_add_u32 s2, s2, s43
	s_addc_u32 s3, s3, 0
	global_load_dword v50, v7, s[2:3]
	s_add_u32 s2, s2, s43
	s_addc_u32 s3, s3, 0
	global_load_dword v51, v7, s[2:3]
	v_add_u32_e32 v10, s42, v4
	s_cmp_eq_u32 s28, 0
	s_cselect_b64 vcc, -1, 0
	s_add_i32 s43, s28, -1
	s_lshl_b32 s43, s43, 7
	v_lshlrev_b32_e32 v11, 3, v3
	v_add_lshl_u32 v11, v11, s29, 1
	v_add_u32_e32 v16, 0, v10
	v_lshrrev_b32_e32 v17, 7, v16
	v_and_b32_e32 v18, 0x7f, v16
	v_lshl_add_u32 v17, v17, 8, v18
	v_add_u32_e32 v17, s43, v17
	v_cndmask_b32_e32 v16, v17, v16, vcc
	v_mul_lo_u32 v16, v16, s13
	v_add_u32_e32 v12, v16, v11
	v_add_u32_e32 v16, 8, v10
	v_lshrrev_b32_e32 v17, 7, v16
	v_and_b32_e32 v18, 0x7f, v16
	v_lshl_add_u32 v17, v17, 8, v18
	v_add_u32_e32 v17, s43, v17
	v_cndmask_b32_e32 v16, v17, v16, vcc
	v_mul_lo_u32 v16, v16, s13
	v_add_u32_e32 v13, v16, v11
	v_add_u32_e32 v16, 16, v10
	v_lshrrev_b32_e32 v17, 7, v16
	v_and_b32_e32 v18, 0x7f, v16
	v_lshl_add_u32 v17, v17, 8, v18
	v_add_u32_e32 v17, s43, v17
	v_cndmask_b32_e32 v16, v17, v16, vcc
	v_mul_lo_u32 v16, v16, s13
	v_add_u32_e32 v14, v16, v11
	v_add_u32_e32 v16, 24, v10
	v_lshrrev_b32_e32 v17, 7, v16
	v_and_b32_e32 v18, 0x7f, v16
	v_lshl_add_u32 v17, v17, 8, v18
	v_add_u32_e32 v17, s43, v17
	v_cndmask_b32_e32 v16, v17, v16, vcc
	v_mul_lo_u32 v16, v16, s13
	v_add_u32_e32 v15, v16, v11
	s_waitcnt vmcnt(0)
; #define LAS __attribute__((address_space(3)))
; __device__ __forceinline__ unsigned pk2(float lo, float hi) { const f32x2 v = {lo, hi}; const bf16x2_t b = __builtin_convertvector(v, bf16x2_t); return __builtin_bit_cast(unsigned, b); }
; __device__ __forceinline__ int map13(int hidden, int which) { return (hidden >> 7) * 256 + which * 128 + (hidden & 127); }
; __device__ __forceinline__ void transpose_item(const float* W, int K, int N, const float* gain, bf16_t* WT, int mode, LAS float* scr, int item, int lane) {
;     ...
;     for (int i = 0; i < 32; ++i) { const int kk = 2 * i + (lane >> 5); float w = W[(size_t)(k0 + kk) * N + n0 + (lane & 31)]; if (gain) w *= gain[k0 + kk]; scr[kk * 33 + (lane & 31)] = w; }
;     asm volatile("s_waitcnt lgkmcnt(0)" ::: "memory");
;     const int c = lane & 7;
; #pragma unroll
;     for (int j = 0; j < 4; ++j) { const int n = (lane >> 3) + 8 * j; const LAS float* s = scr + (8 * c) * 33 + n;
;         u32x4 o; o.x = pk2(s[0 * 33], s[1 * 33]); o.y = pk2(s[2 * 33], s[3 * 33]); o.z = pk2(s[4 * 33], s[5 * 33]); o.w = pk2(s[6 * 33], s[7 * 33]);
;         const int row = (mode == 0) ? (n0 + n) : map13(n0 + n, mode - 1);
;         *(u32x4*)(WT + (size_t)row * K + k0 + 8 * c) = o; }
;     asm volatile("s_waitcnt lgkmcnt(0)" ::: "memory");
	ds_write_b32 v5, v20 offset:0
	ds_write_b32 v5, v21 offset:264
	ds_write_b32 v5, v22 offset:528
	ds_write_b32 v5, v23 offset:792
	ds_write_b32 v5, v24 offset:1056
	ds_write_b32 v5, v25 offset:1320
	ds_write_b32 v5, v26 offset:1584
	ds_write_b32 v5, v27 offset:1848
	ds_write_b32 v5, v28 offset:2112
	ds_write_b32 v5, v29 offset:2376
	ds_write_b32 v5, v30 offset:2640
	ds_write_b32 v5, v31 offset:2904
	s_waitcnt lgkmcnt(0)
	ds_write_b32 v5, v32 offset:3168
	ds_write_b32 v5, v33 offset:3432
	ds_write_b32 v5, v34 offset:3696
	ds_write_b32 v5, v35 offset:3960
	ds_write_b32 v5, v36 offset:4224
	ds_write_b32 v5, v37 offset:4488
	ds_write_b32 v5, v38 offset:4752
	ds_write_b32 v5, v39 offset:5016
	ds_write_b32 v5, v40 offset:5280
	ds_write_b32 v5, v41 offset:5544
	ds_write_b32 v5, v42 offset:5808
	ds_write_b32 v5, v43 offset:6072
	s_waitcnt lgkmcnt(0)
	ds_write_b32 v5, v44 offset:6336
	ds_write_b32 v5, v45 offset:6600
	ds_write_b32 v5, v46 offset:6864
	ds_write_b32 v5, v47 offset:7128
	ds_write_b32 v5, v48 offset:7392
	ds_write_b32 v5, v49 offset:7656
	ds_write_b32 v5, v50 offset:7920
	ds_write_b32 v5, v51 offset:8184
	s_waitcnt lgkmcnt(0)
	ds_read_b32 v60, v6 offset:0
	ds_read_b32 v61, v6 offset:132
	ds_read_b32 v62, v6 offset:264
	ds_read_b32 v63, v6 offset:396
	ds_read_b32 v64, v6 offset:528
	ds_read_b32 v65, v6 offset:660
	ds_read_b32 v66, v6 offset:792
	ds_read_b32 v67, v6 offset:924
	s_waitcnt lgkmcnt(0)
	ds_read_b32 v68, v6 offset:32
	ds_read_b32 v69, v6 offset:164
	ds_read_b32 v70, v6 offset:296
	ds_read_b32 v71, v6 offset:428
	ds_read_b32 v72, v6 offset:560
	ds_read_b32 v73, v6 offset:692
	ds_read_b32 v74, v6 offset:824
	ds_read_b32 v75, v6 offset:956
	v_mul_f32_e32 v60, v60, v52
	v_mul_f32_e32 v61, v61, v53
	v_mul_f32_e32 v62, v62, v54
	v_mul_f32_e32 v63, v63, v55
	v_mul_f32_e32 v64, v64, v56
	v_mul_f32_e32 v65, v65, v57
	v_mul_f32_e32 v66, v66, v58
	v_mul_f32_e32 v67, v67, v59
	v_cvt_pk_bf16_f32 v92, v60, v61
	v_cvt_pk_bf16_f32 v93, v62, v63
	v_cvt_pk_bf16_f32 v94, v64, v65
	v_cvt_pk_bf16_f32 v95, v66, v67
	global_store_dwordx4 v12, v[92:95], s[4:5]
	s_waitcnt lgkmcnt(0)
	ds_read_b32 v76, v6 offset:64
	ds_read_b32 v77, v6 offset:196
	ds_read_b32 v78, v6 offset:328
	ds_read_b32 v79, v6 offset:460
	ds_read_b32 v80, v6 offset:592
	ds_read_b32 v81, v6 offset:724
	ds_read_b32 v82, v6 offset:856
	ds_read_b32 v83, v6 offset:988
	v_mul_f32_e32 v68, v68, v52
	v_mul_f32_e32 v69, v69, v53
	v_mul_f32_e32 v70, v70, v54
	v_mul_f32_e32 v71, v71, v55
	v_mul_f32_e32 v72, v72, v56
	v_mul_f32_e32 v73, v73, v57
	v_mul_f32_e32 v74, v74, v58
	v_mul_f32_e32 v75, v75, v59
	v_cvt_pk_bf16_f32 v96, v68, v69
	v_cvt_pk_bf16_f32 v97, v70, v71
	v_cvt_pk_bf16_f32 v98, v72, v73
	v_cvt_pk_bf16_f32 v99, v74, v75
	global_store_dwordx4 v13, v[96:99], s[4:5]
	s_waitcnt lgkmcnt(0)
	ds_read_b32 v84, v6 offset:96
	ds_read_b32 v85, v6 offset:228
	ds_read_b32 v86, v6 offset:360
	ds_read_b32 v87, v6 offset:492
	ds_read_b32 v88, v6 offset:624
	ds_read_b32 v89, v6 offset:756
	ds_read_b32 v90, v6 offset:888
	ds_read_b32 v91, v6 offset:1020
	v_mul_f32_e32 v76, v76, v52
	v_mul_f32_e32 v77, v77, v53
	v_mul_f32_e32 v78, v78, v54
	v_mul_f32_e32 v79, v79, v55
	v_mul_f32_e32 v80, v80, v56
	v_mul_f32_e32 v81, v81, v57
	v_mul_f32_e32 v82, v82, v58
	v_mul_f32_e32 v83, v83, v59
	v_cvt_pk_bf16_f32 v20, v76, v77
	v_cvt_pk_bf16_f32 v21, v78, v79
	v_cvt_pk_bf16_f32 v22, v80, v81
	v_cvt_pk_bf16_f32 v23, v82, v83
	global_store_dwordx4 v14, v[20:23], s[4:5]
	s_waitcnt lgkmcnt(0)
	v_mul_f32_e32 v84, v84, v52
	v_mul_f32_e32 v85, v85, v53
	v_mul_f32_e32 v86, v86, v54
	v_mul_f32_e32 v87, v87, v55
	v_mul_f32_e32 v88, v88, v56
	v_mul_f32_e32 v89, v89, v57
	v_mul_f32_e32 v90, v90, v58
	v_mul_f32_e32 v91, v91, v59
	v_cvt_pk_bf16_f32 v24, v84, v85
	v_cvt_pk_bf16_f32 v25, v86, v87
	v_cvt_pk_bf16_f32 v26, v88, v89
	v_cvt_pk_bf16_f32 v27, v90, v91
	global_store_dwordx4 v15, v[24:27], s[4:5]
	s_add_i32 s7, s7, s11
	s_branch .Lmy_c9_loop
